# hgrn_scan: the read-once f32 local-state (SL) loads carry the nt streaming hint; on top of write-through GEMM tile stores without barrier write-back (P1,P5,P6,P11,P12) and flat barrier release
# speedup vs baseline: 1.0098x; 1.0098x over previous
; #define GAS __attribute__((address_space(1)))
; __device__ __forceinline__ unsigned pk2(float lo, float hi) { f32x2 v = {lo, hi}; bf16x2_t b = __builtin_convertvector(v, bf16x2_t); return __builtin_bit_cast(unsigned, b); }
; __device__ __forceinline__ void hgrn_scan(Frame& F) {
;     ...
;     for (int idx = F.bid * 512 + F.tid; idx < 32 * 128 * 32; idx += F.G * 512) {
;         const int bh = idx >> 12, v = (idx >> 5) & 127, k = (idx & 31) * 4;
;         f32x4 s = (f32x4){0.f, 0.f, 0.f, 0.f};
; #pragma unroll 4
;         for (int j = 0; j < 16; ++j) { const int it = bh * 16 + j;
;             *(GAS v2u*)(SS + (size_t)it * 16384 + v * 128 + k) = (v2u){pk2(s.x, s.y), pk2(s.z, s.w)};
;             const f32x4 d = *(const GAS f32x4*)(DT + it * 128 + k), sl = *(const GAS f32x4*)(SL + (size_t)it * 16384 + v * 128 + k);
;             s = d * s + sl; }
.LBB0_745:
	v_lshlrev_b32_e32 v4, 4, v16
	v_and_b32_e32 v12, 0xfe00, v4
	v_lshlrev_b32_e32 v4, 3, v16
	v_and_b32_e32 v13, 0x7f00, v4
	v_lshlrev_b32_e32 v4, 1, v17
	v_and_b32_e32 v14, 0xf8, v4
	v_ashrrev_i32_e32 v4, 12, v16
	v_lshlrev_b32_e32 v10, 4, v4
	v_lshlrev_b32_e32 v6, 11, v4
	v_lshlrev_b32_e32 v2, 2, v17
	v_ashrrev_i32_e32 v7, 31, v6
	v_ashrrev_i32_e32 v11, 31, v10
	v_and_b32_e32 v5, 0x1f0, v2
	v_lshlrev_b64 v[6:7], 2, v[6:7]
	v_lshlrev_b64 v[8:9], 16, v[10:11]
	v_lshlrev_b64 v[10:11], 15, v[10:11]
	v_lshrrev_b32_e32 v2, 5, v16
	v_or_b32_e32 v6, v6, v5
	v_or3_b32 v8, v8, v12, v5
	v_or3_b32 v10, v10, v13, v14
	s_mov_b32 s34, 16
	v_mov_b32_e32 v14, 0
	v_mov_b32_e32 v15, v3
	v_mov_b32_e32 v12, 0
	v_mov_b32_e32 v13, v3
	s_waitcnt vmcnt(0)
	s_mov_b64 s[98:99], 0x10000
	s_mov_b64 s[100:101], 0x8000
	s_mov_b32 s34, 0x18a00000
	s_mov_b32 s35, 0
	v_lshl_add_u64 v[26:27], s[30:31], 0, v[6:7]
	v_lshl_add_u64 v[26:27], v[26:27], 0, s[34:35]
	s_mov_b32 s34, 0x16a00000
	v_lshl_add_u64 v[28:29], s[30:31], 0, v[8:9]
	v_lshl_add_u64 v[28:29], v[28:29], 0, s[34:35]
	s_mov_b32 s34, 0x18b00000
	v_lshl_add_u64 v[30:31], s[30:31], 0, v[10:11]
	v_lshl_add_u64 v[30:31], v[30:31], 0, s[34:35]
	s_mov_b64 s[34:35], 0x1000
	global_load_dwordx4 v[180:183], v[26:27], off
	global_load_dwordx4 v[184:187], v[26:27], off offset:512
	global_load_dwordx4 v[188:191], v[26:27], off offset:1024
	global_load_dwordx4 v[192:195], v[26:27], off offset:1536
	global_load_dwordx4 v[196:199], v[26:27], off offset:2048
	global_load_dwordx4 v[200:203], v[26:27], off offset:2560
	global_load_dwordx4 v[204:207], v[26:27], off offset:3072
	global_load_dwordx4 v[208:211], v[26:27], off offset:3584
	v_lshl_add_u64 v[26:27], v[26:27], 0, s[34:35]
	global_load_dwordx4 v[212:215], v[28:29], off nt
	v_lshl_add_u64 v[28:29], v[28:29], 0, s[98:99]
	global_load_dwordx4 v[216:219], v[28:29], off nt
	v_lshl_add_u64 v[28:29], v[28:29], 0, s[98:99]
	global_load_dwordx4 v[220:223], v[28:29], off nt
	v_lshl_add_u64 v[28:29], v[28:29], 0, s[98:99]
	global_load_dwordx4 v[224:227], v[28:29], off nt
	v_lshl_add_u64 v[28:29], v[28:29], 0, s[98:99]
	global_load_dwordx4 v[228:231], v[28:29], off nt
	v_lshl_add_u64 v[28:29], v[28:29], 0, s[98:99]
	global_load_dwordx4 v[232:235], v[28:29], off nt
	v_lshl_add_u64 v[28:29], v[28:29], 0, s[98:99]
	global_load_dwordx4 v[236:239], v[28:29], off nt
	v_lshl_add_u64 v[28:29], v[28:29], 0, s[98:99]
	global_load_dwordx4 v[240:243], v[28:29], off nt
	v_lshl_add_u64 v[28:29], v[28:29], 0, s[98:99]
	s_waitcnt vmcnt(7)
	v_cvt_pk_bf16_f32 v18, v14, v15
	v_cvt_pk_bf16_f32 v19, v12, v13
	global_store_dwordx2 v[30:31], v[18:19], off
	v_lshl_add_u64 v[30:31], v[30:31], 0, s[100:101]
	v_pk_fma_f32 v[14:15], v[14:15], v[180:181], v[212:213]
	v_pk_fma_f32 v[12:13], v[12:13], v[182:183], v[214:215]
	s_waitcnt vmcnt(7)
	v_cvt_pk_bf16_f32 v18, v14, v15
	v_cvt_pk_bf16_f32 v19, v12, v13
	global_store_dwordx2 v[30:31], v[18:19], off
	v_lshl_add_u64 v[30:31], v[30:31], 0, s[100:101]
	v_pk_fma_f32 v[14:15], v[14:15], v[184:185], v[216:217]
	v_pk_fma_f32 v[12:13], v[12:13], v[186:187], v[218:219]
	s_waitcnt vmcnt(7)
	v_cvt_pk_bf16_f32 v18, v14, v15
	v_cvt_pk_bf16_f32 v19, v12, v13
	global_store_dwordx2 v[30:31], v[18:19], off
	v_lshl_add_u64 v[30:31], v[30:31], 0, s[100:101]
	v_pk_fma_f32 v[14:15], v[14:15], v[188:189], v[220:221]
	v_pk_fma_f32 v[12:13], v[12:13], v[190:191], v[222:223]
	s_waitcnt vmcnt(7)
	v_cvt_pk_bf16_f32 v18, v14, v15
	v_cvt_pk_bf16_f32 v19, v12, v13
	global_store_dwordx2 v[30:31], v[18:19], off
	v_lshl_add_u64 v[30:31], v[30:31], 0, s[100:101]
	v_pk_fma_f32 v[14:15], v[14:15], v[192:193], v[224:225]
	v_pk_fma_f32 v[12:13], v[12:13], v[194:195], v[226:227]
	s_waitcnt vmcnt(7)
	v_cvt_pk_bf16_f32 v18, v14, v15
	v_cvt_pk_bf16_f32 v19, v12, v13
	global_store_dwordx2 v[30:31], v[18:19], off
	v_lshl_add_u64 v[30:31], v[30:31], 0, s[100:101]
	v_pk_fma_f32 v[14:15], v[14:15], v[196:197], v[228:229]
	v_pk_fma_f32 v[12:13], v[12:13], v[198:199], v[230:231]
	s_waitcnt vmcnt(7)
	v_cvt_pk_bf16_f32 v18, v14, v15
	v_cvt_pk_bf16_f32 v19, v12, v13
	global_store_dwordx2 v[30:31], v[18:19], off
	v_lshl_add_u64 v[30:31], v[30:31], 0, s[100:101]
	v_pk_fma_f32 v[14:15], v[14:15], v[200:201], v[232:233]
	v_pk_fma_f32 v[12:13], v[12:13], v[202:203], v[234:235]
	s_waitcnt vmcnt(7)
	v_cvt_pk_bf16_f32 v18, v14, v15
	v_cvt_pk_bf16_f32 v19, v12, v13
	global_store_dwordx2 v[30:31], v[18:19], off
	v_lshl_add_u64 v[30:31], v[30:31], 0, s[100:101]
	v_pk_fma_f32 v[14:15], v[14:15], v[204:205], v[236:237]
	v_pk_fma_f32 v[12:13], v[12:13], v[206:207], v[238:239]
	s_waitcnt vmcnt(7)
; #define GAS __attribute__((address_space(1)))
; __device__ __forceinline__ unsigned pk2(float lo, float hi) { f32x2 v = {lo, hi}; bf16x2_t b = __builtin_convertvector(v, bf16x2_t); return __builtin_bit_cast(unsigned, b); }
; __device__ __forceinline__ void hgrn_scan(Frame& F) {
;     ...
;         for (int j = 0; j < 16; ++j) { const int it = bh * 16 + j;
;             *(GAS v2u*)(SS + (size_t)it * 16384 + v * 128 + k) = (v2u){pk2(s.x, s.y), pk2(s.z, s.w)};
;             const f32x4 d = *(const GAS f32x4*)(DT + it * 128 + k), sl = *(const GAS f32x4*)(SL + (size_t)it * 16384 + v * 128 + k);
;             s = d * s + sl; }
; #pragma unroll
;         for (int e = 0; e < 4; ++e) SHP[(size_t)bh * 16384 + (k + e) * 128 + v] = s[e];
;     }
	v_cvt_pk_bf16_f32 v18, v14, v15
	v_cvt_pk_bf16_f32 v19, v12, v13
	global_store_dwordx2 v[30:31], v[18:19], off
	v_lshl_add_u64 v[30:31], v[30:31], 0, s[100:101]
	v_pk_fma_f32 v[14:15], v[14:15], v[208:209], v[240:241]
	v_pk_fma_f32 v[12:13], v[12:13], v[210:211], v[242:243]
	s_nop 1
	global_load_dwordx4 v[180:183], v[26:27], off
	global_load_dwordx4 v[184:187], v[26:27], off offset:512
	global_load_dwordx4 v[188:191], v[26:27], off offset:1024
	global_load_dwordx4 v[192:195], v[26:27], off offset:1536
	global_load_dwordx4 v[196:199], v[26:27], off offset:2048
	global_load_dwordx4 v[200:203], v[26:27], off offset:2560
	global_load_dwordx4 v[204:207], v[26:27], off offset:3072
	global_load_dwordx4 v[208:211], v[26:27], off offset:3584
	v_lshl_add_u64 v[26:27], v[26:27], 0, s[34:35]
	global_load_dwordx4 v[212:215], v[28:29], off nt
	v_lshl_add_u64 v[28:29], v[28:29], 0, s[98:99]
	global_load_dwordx4 v[216:219], v[28:29], off nt
	v_lshl_add_u64 v[28:29], v[28:29], 0, s[98:99]
	global_load_dwordx4 v[220:223], v[28:29], off nt
	v_lshl_add_u64 v[28:29], v[28:29], 0, s[98:99]
	global_load_dwordx4 v[224:227], v[28:29], off nt
	v_lshl_add_u64 v[28:29], v[28:29], 0, s[98:99]
	global_load_dwordx4 v[228:231], v[28:29], off nt
	v_lshl_add_u64 v[28:29], v[28:29], 0, s[98:99]
	global_load_dwordx4 v[232:235], v[28:29], off nt
	v_lshl_add_u64 v[28:29], v[28:29], 0, s[98:99]
	global_load_dwordx4 v[236:239], v[28:29], off nt
	v_lshl_add_u64 v[28:29], v[28:29], 0, s[98:99]
	global_load_dwordx4 v[240:243], v[28:29], off nt
	v_lshl_add_u64 v[28:29], v[28:29], 0, s[98:99]
	s_waitcnt vmcnt(7)
	v_cvt_pk_bf16_f32 v18, v14, v15
	v_cvt_pk_bf16_f32 v19, v12, v13
	global_store_dwordx2 v[30:31], v[18:19], off
	v_lshl_add_u64 v[30:31], v[30:31], 0, s[100:101]
	v_pk_fma_f32 v[14:15], v[14:15], v[180:181], v[212:213]
	v_pk_fma_f32 v[12:13], v[12:13], v[182:183], v[214:215]
	s_waitcnt vmcnt(7)
	v_cvt_pk_bf16_f32 v18, v14, v15
	v_cvt_pk_bf16_f32 v19, v12, v13
	global_store_dwordx2 v[30:31], v[18:19], off
	v_lshl_add_u64 v[30:31], v[30:31], 0, s[100:101]
	v_pk_fma_f32 v[14:15], v[14:15], v[184:185], v[216:217]
	v_pk_fma_f32 v[12:13], v[12:13], v[186:187], v[218:219]
	s_waitcnt vmcnt(7)
	v_cvt_pk_bf16_f32 v18, v14, v15
	v_cvt_pk_bf16_f32 v19, v12, v13
	global_store_dwordx2 v[30:31], v[18:19], off
	v_lshl_add_u64 v[30:31], v[30:31], 0, s[100:101]
	v_pk_fma_f32 v[14:15], v[14:15], v[188:189], v[220:221]
	v_pk_fma_f32 v[12:13], v[12:13], v[190:191], v[222:223]
	s_waitcnt vmcnt(7)
	v_cvt_pk_bf16_f32 v18, v14, v15
	v_cvt_pk_bf16_f32 v19, v12, v13
	global_store_dwordx2 v[30:31], v[18:19], off
	v_lshl_add_u64 v[30:31], v[30:31], 0, s[100:101]
	v_pk_fma_f32 v[14:15], v[14:15], v[192:193], v[224:225]
	v_pk_fma_f32 v[12:13], v[12:13], v[194:195], v[226:227]
	s_waitcnt vmcnt(7)
	v_cvt_pk_bf16_f32 v18, v14, v15
	v_cvt_pk_bf16_f32 v19, v12, v13
	global_store_dwordx2 v[30:31], v[18:19], off
	v_lshl_add_u64 v[30:31], v[30:31], 0, s[100:101]
	v_pk_fma_f32 v[14:15], v[14:15], v[196:197], v[228:229]
	v_pk_fma_f32 v[12:13], v[12:13], v[198:199], v[230:231]
	s_waitcnt vmcnt(7)
	v_cvt_pk_bf16_f32 v18, v14, v15
	v_cvt_pk_bf16_f32 v19, v12, v13
	global_store_dwordx2 v[30:31], v[18:19], off
	v_lshl_add_u64 v[30:31], v[30:31], 0, s[100:101]
	v_pk_fma_f32 v[14:15], v[14:15], v[200:201], v[232:233]
	v_pk_fma_f32 v[12:13], v[12:13], v[202:203], v[234:235]
	s_waitcnt vmcnt(7)
	v_cvt_pk_bf16_f32 v18, v14, v15
	v_cvt_pk_bf16_f32 v19, v12, v13
	global_store_dwordx2 v[30:31], v[18:19], off
	v_lshl_add_u64 v[30:31], v[30:31], 0, s[100:101]
	v_pk_fma_f32 v[14:15], v[14:15], v[204:205], v[236:237]
	v_pk_fma_f32 v[12:13], v[12:13], v[206:207], v[238:239]
	s_waitcnt vmcnt(7)
	v_cvt_pk_bf16_f32 v18, v14, v15
	v_cvt_pk_bf16_f32 v19, v12, v13
	global_store_dwordx2 v[30:31], v[18:19], off
	v_lshl_add_u64 v[30:31], v[30:31], 0, s[100:101]
	v_pk_fma_f32 v[14:15], v[14:15], v[208:209], v[240:241]
	v_pk_fma_f32 v[12:13], v[12:13], v[210:211], v[242:243]
	v_ashrrev_i32_e32 v5, 31, v4
	v_and_b32_e32 v2, 0x7f, v2
	v_lshlrev_b64 v[4:5], 16, v[4:5]
	v_lshl_add_u64 v[4:5], s[6:7], 0, v[4:5]
	v_lshlrev_b32_e32 v2, 2, v2
	v_lshl_add_u64 v[4:5], v[4:5], 0, v[2:3]
	v_lshlrev_b32_e32 v2, 11, v16
	v_add_u32_e32 v16, s0, v16
	v_and_b32_e32 v2, 0xf800, v2
	v_cmp_lt_i32_e32 vcc, s33, v16
	v_lshl_add_u64 v[4:5], v[4:5], 0, v[2:3]
	s_or_b64 s[8:9], vcc, s[8:9]
	v_add_u32_e32 v17, s1, v17
	global_store_dword v[4:5], v14, off
	global_store_dword v[4:5], v15, off offset:512
	global_store_dword v[4:5], v12, off offset:1024
	global_store_dword v[4:5], v13, off offset:1536
	s_andn2_b64 exec, exec, s[8:9]
	s_cbranch_execnz .LBB0_745
